# S5 operator set-up moved between arriving at and waiting for the kernel-start grid sync (item = workgroup id), out of the attention tail
# speedup vs baseline: 1.0077x; 1.0033x over previous
.LBB0_20:
	s_or_b64 exec, exec, s[10:11]
	v_and_b32_e32 v1, 0xffff0000, v1
	s_nop 0
	v_readfirstlane_b32 s99, v1
.Lgs_arrived:
	s_or_b64 exec, exec, s[6:7]
	v_cmp_eq_u32_e64 s[26:27], 0, v208
	v_and_b32_e32 v210, 63, v208

.Lssa_450:
	s_and_saveexec_b64 s[4:5], s[26:27]
	s_cbranch_execz .Lssa_454
	s_mov_b64 s[84:85], exec
	v_mbcnt_lo_u32_b32 v4, s84, 0
	v_mbcnt_hi_u32_b32 v4, s85, v4
	v_cmp_eq_u32_e32 vcc, 0, v4
	s_and_saveexec_b64 s[82:83], vcc
	s_cbranch_execz .Lssa_453
	s_bcnt1_i32_b64 s84, s[84:85]
	v_mov_b32_e32 v5, s84
	v_mov_b32_e32 v5, s2

.Lssa_exit:
	v_readfirstlane_b32 s79, v208
	v_cmp_gt_u32_e64 s[4:5], 32, v208
	s_and_saveexec_b64 s[6:7], s[26:27]
	s_cbranch_execz .LBB0_24
	s_load_dwordx2 s[8:9], s[0:1], 0x110
	v_mov_b32_e32 v0, 0
	v_mov_b32_e32 v1, s99
	s_waitcnt lgkmcnt(0)
	global_load_dword v2, v0, s[8:9] offset:32 sc1
	s_waitcnt vmcnt(0)
	v_and_b32_e32 v2, 0xffff0000, v2
	v_cmp_eq_u32_e32 vcc, v2, v1
	s_and_b64 exec, exec, vcc
	s_cbranch_execz .LBB0_23
	s_mov_b64 s[10:11], 0

.LBB0_24:
	s_or_b64 exec, exec, s[6:7]
	s_mov_b64 s[6:7], s[0:1]
	s_barrier
	s_load_dwordx2 s[30:31], s[6:7], 0xa8
	s_getreg_b32 s60, hwreg(HW_REG_XCC_ID, 0, 4)
	v_cmp_eq_u32_e64 s[26:27], 0, v208
	s_waitcnt lgkmcnt(0)
	s_add_u32 s34, s30, 0x40000
	s_addc_u32 s35, s31, 0
	s_and_b32 s33, s60, 15
	s_and_saveexec_b64 s[6:7], s[26:27]
	s_cbranch_execz .LBB0_27
	s_mov_b64 s[8:9], exec
	v_mbcnt_lo_u32_b32 v0, s8, 0
	v_mbcnt_hi_u32_b32 v0, s9, v0
	v_cmp_eq_u32_e32 vcc, 0, v0
	s_and_b64 s[10:11], exec, vcc
	s_mov_b64 exec, s[10:11]
	s_cbranch_execz .LBB0_27
	s_lshl_b32 s10, s33, 8
	s_bcnt1_i32_b64 s8, s[8:9]
	v_mov_b32_e32 v0, s10
	v_mov_b32_e32 v1, s8
	global_atomic_add v0, v1, s[34:35] offset:1024
	v_mov_b32_e32 v0, 0x4800
	v_mov_b32_e32 v1, 1
	global_atomic_add v0, v1, s[34:35]
	s_lshl_b32 s98, s2, 2
	s_add_i32 s98, s98, 0x8000
	v_mov_b32_e32 v0, s98
	v_mov_b32_e32 v1, s33
	global_store_dword v0, v1, s[34:35]
